# MLA loop variant: K fragment reads early, restaging and global loads behind the first three MFMA steps
# baseline (speedup 1.0000x reference)
.LBB0_190:
	s_bitcmp1_b32 s1, 0
	s_cselect_b32 s0, 0x5400, 0
	v_add3_u32 v185, s0, v192, v159
	ds_read_b128 v[186:189], v185
	ds_read_b128 v[194:197], v185 offset:64
	ds_read_b128 v[202:205], v185 offset:128
	ds_read_b128 v[112:115], v185 offset:832
	ds_read_b128 v[108:111], v185 offset:896
	ds_read_b128 v[104:107], v185 offset:960
	v_add_u32_e32 v100, s0, v174
	v_add3_u32 v100, v100, v175, v176
	v_add_u32_e32 v184, v100, v177
	v_add_u32_e32 v183, v100, v178
	v_add_u32_e32 v182, v100, v179
	v_add_u32_e32 v181, v100, v180
	ds_read_b128 v[100:103], v185 offset:6656
	ds_read_b128 v[144:147], v185 offset:6720
	ds_read_b128 v[128:131], v185 offset:6784
	s_waitcnt lgkmcnt(8)
	v_mfma_f32_16x16x32_bf16 v[136:139], v[186:189], v[12:15], v[36:39]
	v_mfma_f32_16x16x32_bf16 v[120:123], v[186:189], v[20:23], v[48:51]
	ds_read_b128 v[186:189], v185 offset:7488
	s_waitcnt lgkmcnt(8)
	v_mfma_f32_16x16x32_bf16 v[136:139], v[194:197], v[16:19], v[136:139]
	v_mfma_f32_16x16x32_bf16 v[120:123], v[194:197], v[24:27], v[120:123]
	ds_read_b128 v[194:197], v185 offset:7552
	s_waitcnt lgkmcnt(8)
	v_mfma_f32_16x16x32_bf16 v[136:139], v[202:205], v[0:3], v[136:139]
	v_mfma_f32_16x16x32_bf16 v[120:123], v[202:205], v[4:7], v[120:123]
	ds_read_b128 v[202:205], v185 offset:7616
	s_andn2_b32 s0, 1, s1
	s_mulk_i32 s0, 0x5400
	s_add_i32 s10, s1, 1
	v_add3_u32 v140, s0, v151, v155
	v_add3_u32 v141, s0, v157, v170
	v_add_u32_e32 v142, s0, v171
	s_waitcnt vmcnt(2)
	ds_write_b128 v140, v[8:11]
	v_add3_u32 v142, v142, v173, v172
	s_add_i32 s0, s1, 3
	s_min_u32 s0, s0, s83
	s_waitcnt vmcnt(0)
	ds_write_b128 v141, v[28:31]
	s_lshl_b32 s0, s0, 6
	ds_write_b128 v142, v[32:35] offset:13312
	v_add_u32_e32 v8, s0, v154
	v_add_u32_e32 v28, s0, v156
	s_add_i32 s0, s1, 2
	v_ashrrev_i32_e32 v9, 31, v8
	v_ashrrev_i32_e32 v29, 31, v28
	s_min_u32 s0, s0, s83
	v_lshlrev_b64 v[10:11], 11, v[8:9]
	v_lshlrev_b64 v[8:9], 6, v[8:9]
	v_lshlrev_b64 v[30:31], 11, v[28:29]
	v_lshlrev_b64 v[28:29], 6, v[28:29]
	v_lshl_add_u32 v32, s0, 6, v158
	v_lshl_add_u64 v[8:9], v[162:163], 0, v[8:9]
	v_lshl_add_u64 v[28:29], v[166:167], 0, v[28:29]
	v_ashrrev_i32_e32 v33, 31, v32
	v_lshl_add_u64 v[10:11], v[164:165], 0, v[10:11]
	v_lshl_add_u64 v[8:9], v[8:9], 0, s[58:59]
	v_lshl_add_u64 v[30:31], v[168:169], 0, v[30:31]
	v_lshl_add_u64 v[28:29], v[28:29], 0, s[58:59]
	v_lshlrev_b64 v[32:33], 11, v[32:33]
	v_cndmask_b32_e64 v9, v9, v11, s[6:7]
	v_cndmask_b32_e64 v8, v8, v10, s[6:7]
	v_cndmask_b32_e64 v29, v29, v31, s[8:9]
	v_cndmask_b32_e64 v28, v28, v30, s[8:9]
	v_lshl_add_u64 v[32:33], v[160:161], 0, v[32:33]
	global_load_dwordx4 v[8:11], v[8:9], off
	global_load_dwordx4 v[28:31], v[28:29], off
	global_load_dwordx4 v[32:35], v[32:33], off offset:128
	s_waitcnt lgkmcnt(11)
	v_mfma_f32_16x16x32_bf16 v[132:135], v[112:115], v[12:15], v[36:39]
	v_mfma_f32_16x16x32_bf16 v[116:119], v[112:115], v[20:23], v[48:51]
	ds_read_b64_tr_b16 v[112:113], v184 offset:13312
	ds_read_b64_tr_b16 v[114:115], v184 offset:13824
	s_waitcnt lgkmcnt(12)
	v_mfma_f32_16x16x32_bf16 v[132:135], v[108:111], v[16:19], v[132:135]
	v_mfma_f32_16x16x32_bf16 v[116:119], v[108:111], v[24:27], v[116:119]
	ds_read_b64_tr_b16 v[108:109], v183 offset:13312
	ds_read_b64_tr_b16 v[110:111], v183 offset:13824
	s_waitcnt lgkmcnt(13)
	v_mfma_f32_16x16x32_bf16 v[132:135], v[104:107], v[0:3], v[132:135]
	v_mfma_f32_16x16x32_bf16 v[116:119], v[104:107], v[4:7], v[116:119]
	ds_read_b64_tr_b16 v[104:105], v182 offset:13312
	ds_read_b64_tr_b16 v[106:107], v182 offset:13824
	s_waitcnt lgkmcnt(14)
	v_mfma_f32_16x16x32_bf16 v[140:143], v[100:103], v[12:15], v[36:39]
	v_mfma_f32_16x16x32_bf16 v[124:127], v[100:103], v[20:23], v[48:51]
	ds_read_b64_tr_b16 v[100:101], v181 offset:13312
	ds_read_b64_tr_b16 v[102:103], v181 offset:13824
	s_waitcnt lgkmcnt(15)
	v_mfma_f32_16x16x32_bf16 v[140:143], v[144:147], v[16:19], v[140:143]
	v_mfma_f32_16x16x32_bf16 v[124:127], v[144:147], v[24:27], v[124:127]
	s_waitcnt lgkmcnt(14)
	v_mfma_f32_16x16x32_bf16 v[140:143], v[128:131], v[0:3], v[140:143]
	v_mfma_f32_16x16x32_bf16 v[124:127], v[128:131], v[4:7], v[124:127]
	s_waitcnt lgkmcnt(13)
	v_mfma_f32_16x16x32_bf16 v[144:147], v[186:189], v[12:15], v[36:39]
	v_mfma_f32_16x16x32_bf16 v[128:131], v[186:189], v[20:23], v[48:51]
	s_waitcnt lgkmcnt(12)
	v_mfma_f32_16x16x32_bf16 v[144:147], v[194:197], v[16:19], v[144:147]
	v_mfma_f32_16x16x32_bf16 v[128:131], v[194:197], v[24:27], v[128:131]
	s_waitcnt lgkmcnt(11)
	v_mfma_f32_16x16x32_bf16 v[144:147], v[202:205], v[0:3], v[144:147]
	v_mfma_f32_16x16x32_bf16 v[128:131], v[202:205], v[4:7], v[128:131]
	s_cmp_ge_u32 s10, s82
	s_cbranch_scc1 .LBB0_196
	s_cmp_lg_u32 s1, 0
	s_cselect_b64 s[0:1], -1, 0
	s_and_b32 s11, s10, 3
	s_cmp_lg_u32 s11, 0
	s_cselect_b64 s[14:15], -1, 0
	s_and_b64 s[0:1], s[0:1], s[14:15]
	s_and_b64 vcc, exec, s[0:1]
	s_cbranch_vccnz .LBB0_196
	v_max_f32_e32 v185, v137, v137
	v_max_f32_e32 v186, v136, v136
	v_max_f32_e32 v185, v186, v185
	v_max3_f32 v185, v185, v138, v139
	v_max3_f32 v185, v185, v132, v133
	v_max3_f32 v185, v185, v134, v135
	v_max3_f32 v185, v185, v140, v141
	v_max3_f32 v185, v185, v142, v143
	v_max3_f32 v185, v185, v144, v145
	v_max3_f32 v185, v185, v146, v147
	v_mov_b32_e32 v186, v185
	s_nop 1
	v_permlane16_swap_b32_e32 v185, v186
	v_max_f32_e32 v186, v186, v186
	v_max_f32_e32 v185, v185, v185
	v_max_f32_e32 v185, v185, v186
	v_mov_b32_e32 v186, v185
	s_nop 1
	v_permlane32_swap_b32_e32 v185, v186
	v_max_f32_e32 v186, v186, v186
	v_max_f32_e32 v185, v185, v185
	v_max_f32_e32 v185, v185, v186
	v_cmp_lt_f32_e32 vcc, s44, v185
	s_cbranch_vccz .LBB0_194
	s_nop 0
	v_cndmask_b32_e32 v185, 0, v185, vcc
	v_exp_f32_e64 v186, -v185
	v_lshlrev_b32_e32 v188, 16, v56
	v_and_b32_e32 v189, 0xffff0000, v56
	v_sub_f32_e32 v139, v139, v185
	v_pk_mul_f32 v[188:189], v[186:187], v[188:189] op_sel_hi:[0,1]
	v_cvt_pk_bf16_f32 v56, v188, v189
	v_lshlrev_b32_e32 v188, 16, v57
	v_and_b32_e32 v189, 0xffff0000, v57
	v_pk_mul_f32 v[188:189], v[186:187], v[188:189] op_sel_hi:[0,1]
	v_cvt_pk_bf16_f32 v57, v188, v189
	v_lshlrev_b32_e32 v188, 16, v58
	v_and_b32_e32 v189, 0xffff0000, v58
	v_pk_mul_f32 v[188:189], v[186:187], v[188:189] op_sel_hi:[0,1]
	v_cvt_pk_bf16_f32 v58, v188, v189
	v_lshlrev_b32_e32 v188, 16, v59
	v_and_b32_e32 v189, 0xffff0000, v59
	v_pk_mul_f32 v[188:189], v[186:187], v[188:189] op_sel_hi:[0,1]
	v_cvt_pk_bf16_f32 v59, v188, v189
	v_lshlrev_b32_e32 v188, 16, v52
	v_and_b32_e32 v189, 0xffff0000, v52
	v_pk_mul_f32 v[188:189], v[186:187], v[188:189] op_sel_hi:[0,1]
	v_cvt_pk_bf16_f32 v52, v188, v189
	v_lshlrev_b32_e32 v188, 16, v53
	v_and_b32_e32 v189, 0xffff0000, v53
	v_pk_mul_f32 v[188:189], v[186:187], v[188:189] op_sel_hi:[0,1]
	v_cvt_pk_bf16_f32 v53, v188, v189
	v_lshlrev_b32_e32 v188, 16, v54
	v_and_b32_e32 v189, 0xffff0000, v54
	v_pk_mul_f32 v[188:189], v[186:187], v[188:189] op_sel_hi:[0,1]
	v_cvt_pk_bf16_f32 v54, v188, v189
	v_lshlrev_b32_e32 v188, 16, v55
	v_and_b32_e32 v189, 0xffff0000, v55
	v_pk_mul_f32 v[78:79], v[78:79], v[186:187] op_sel_hi:[1,0]
	v_pk_mul_f32 v[76:77], v[76:77], v[186:187] op_sel_hi:[1,0]
	v_pk_mul_f32 v[98:99], v[98:99], v[186:187] op_sel_hi:[1,0]
	v_pk_mul_f32 v[96:97], v[96:97], v[186:187] op_sel_hi:[1,0]
	v_pk_mul_f32 v[94:95], v[94:95], v[186:187] op_sel_hi:[1,0]
	v_pk_mul_f32 v[92:93], v[92:93], v[186:187] op_sel_hi:[1,0]
	v_pk_mul_f32 v[86:87], v[86:87], v[186:187] op_sel_hi:[1,0]
	v_pk_mul_f32 v[84:85], v[84:85], v[186:187] op_sel_hi:[1,0]
	v_pk_mul_f32 v[42:43], v[42:43], v[186:187] op_sel_hi:[1,0]
	v_pk_mul_f32 v[40:41], v[40:41], v[186:187] op_sel_hi:[1,0]
	v_pk_mul_f32 v[186:187], v[186:187], v[188:189] op_sel_hi:[0,1]
	v_sub_f32_e32 v138, v138, v185
	v_sub_f32_e32 v137, v137, v185
	v_sub_f32_e32 v136, v136, v185
	v_sub_f32_e32 v135, v135, v185
	v_sub_f32_e32 v134, v134, v185
	v_sub_f32_e32 v133, v133, v185
	v_sub_f32_e32 v132, v132, v185
	v_sub_f32_e32 v143, v143, v185
	v_sub_f32_e32 v142, v142, v185
	v_sub_f32_e32 v141, v141, v185
	v_sub_f32_e32 v140, v140, v185
	v_sub_f32_e32 v147, v147, v185
	v_sub_f32_e32 v146, v146, v185
	v_sub_f32_e32 v145, v145, v185
	v_sub_f32_e32 v144, v144, v185
	v_cvt_pk_bf16_f32 v55, v186, v187
	v_sub_f32_e32 v39, v39, v185
	v_sub_f32_e32 v38, v38, v185
	v_sub_f32_e32 v37, v37, v185
	v_sub_f32_e32 v36, v36, v185
